# P4 epilogue: first wait counted (vmcnt(8): gate values + first batch of x loads), second batch waited for at its first use behind the first stores
# speedup vs baseline: 1.0077x; 1.0077x over previous
; #define PG8_STAGE(bufoff, gbase, voff) do { _Pragma("unroll") for (int _i = 0; _i < 2; ++_i) \
;         __builtin_amdgcn_global_load_lds((const unsigned*)((const char*)(gbase) + (voff)[_i]), (PG8_LAS unsigned*)(lds + (bufoff) + ldsw + _i * 8192), 16, 0, 0); } while (0)
; #define PG8_LDA(dst, b, h) do { _Pragma("unroll") for (int m = 0; m < 4; ++m) _Pragma("unroll") for (int k = 0; k < 2; ++k) dst[m][k] = *(const PG8_LAS bf16x8*)(lds + PG8_SA(b, h) + aoff + m * 2048 + k * 1024); } while (0)
; #define PG8_LDB(dst, b, h) do { _Pragma("unroll") for (int n = 0; n < 2; ++n) _Pragma("unroll") for (int k = 0; k < 2; ++k) dst[n][k] = *(const PG8_LAS bf16x8*)(lds + PG8_SB(b, h) + boff + n * 2048 + k * 1024); } while (0)
; #define PG8_SCHED __builtin_amdgcn_sched_barrier(0)
; #define EO_LOAD(bt_) do { _Pragma("unroll") for (int mm = 0; mm < 2; ++mm) { const float* xr = xbase + (size_t)(row0 + ((bt_) >> 1) * 128 + (2 * ((bt_) & 1) + mm) * 16) * DM + col0; \
;             _Pragma("unroll") for (int bj = 0; bj < 2; ++bj) _Pragma("unroll") for (int n = 0; n < 2; ++n) xv[(bt_) & 1][mm][bj][n] = *(const f32x4*)(xr + 128 * bj + 4 * n); } } while (0)
; #define EO_FENCE() asm volatile("" ::: "memory")
; template <class Epi, class Sched, bool ALIGN_EPI = false, bool SP2 = false>
; __device__ __forceinline__ void gemm_phase(PG8_LAS unsigned char* lds, const Gemm g, const Sched& S, const Epi& E) {
;     ...
;             PG8_LDB(B0, 0, 0); PG8_LDB(B1, 0, 1); PG8_SCHED; PG8_LDA(At, 0, 0); PG8_STAGE(PG8_SA(1, 1), a1 + hstep, voffA);
;     __device__ __forceinline__ void operator()(const f32x4 (&acc)[2][2][4][2], const pg8::Unit& u, int wr, int wc, int fr, int fq) const {
;         const int row0 = u.pm * 256 + wr * 64 + fr, col0 = u.pn * 256 + wc * 32 + 8 * fq;
;         const int s = (u.pm * 256 < NP) ? ((u.pm * 256) >> 12) : 16;
;         const float* gate = mod + s * 3072 + 2048;
;         f32x4 gv[2][2];
; #pragma unroll
;         for (int bj = 0; bj < 2; ++bj)
; #pragma unroll
;             for (int n = 0; n < 2; ++n) gv[bj][n] = *(const f32x4*)(gate + col0 + 128 * bj + 4 * n);
;         const float* xbase = (u.pm * 256 < NP) ? xp : xs - (size_t)NP * DM;
;         f32x4 xv[2][2][2][2];
;     ...
;         EO_LOAD(0); EO_FENCE(); EO_LOAD(1); EO_FENCE();
.LBB0_460:
	s_add_u32 s68, s61, 0x40080
	s_addc_u32 s69, s25, 0
	v_lshl_add_u64 v[164:165], s[68:69], 0, v[152:153]
	s_add_i32 m0, s31, 0xc000
	v_lshl_add_u64 v[216:217], s[68:69], 0, v[154:155]
	global_load_lds_dwordx4 v[164:165], off
	s_add_i32 m0, s31, 0xe000
	s_nop 0
	global_load_lds_dwordx4 v[216:217], off
	s_lshr_b32 s21, s30, 4
	s_cmpk_lt_i32 s30, 0x100
	s_mulk_i32 s21, 0xc00
	s_cselect_b32 s34, s21, 0xc000
	s_cselect_b32 s38, s36, s54
	s_cselect_b32 s39, s37, s55
	s_ashr_i32 s35, s34, 31
	v_lshl_or_b32 v128, s60, 8, v168
	s_lshl_b64 s[34:35], s[34:35], 2
	s_add_u32 s34, s22, s34
	v_ashrrev_i32_e32 v129, 31, v128
	v_lshl_add_u32 v220, s30, 8, v166
	v_and_b32_e32 v220, -2, v220
	s_addc_u32 s35, s23, s35
	v_lshlrev_b64 v[160:161], 2, v[128:129]
	v_or_b32_e32 v188, 16, v220
	v_lshl_add_u64 v[128:129], s[34:35], 0, v[160:161]
	v_ashrrev_i32_e32 v221, 31, v220
	v_ashrrev_i32_e32 v189, 31, v188
	v_or_b32_e32 v204, 32, v220
	v_lshl_add_u64 v[132:133], v[128:129], 0, s[10:11]
	v_add_co_u32_e32 v128, vcc, s52, v128
	v_and_b32_e32 v162, 1, v166
	v_lshlrev_b32_e32 v162, 4, v162
	v_add_u32_e32 v162, 0x800, v162
	v_add_u32_e32 v160, v160, v162
	v_lshl_add_u64 v[162:163], s[38:39], 0, v[160:161]
	v_lshlrev_b64 v[164:165], 12, v[220:221]
	v_lshlrev_b64 v[236:237], 12, v[188:189]
	v_ashrrev_i32_e32 v205, 31, v204
	v_addc_co_u32_e32 v129, vcc, 0, v129, vcc
	v_lshl_add_u64 v[184:185], v[162:163], 0, v[164:165]
	v_lshl_add_u64 v[200:201], v[162:163], 0, v[236:237]
	v_lshlrev_b64 v[238:239], 12, v[204:205]
	global_load_dwordx4 v[136:139], v[128:129], off
	s_nop 0
	global_load_dwordx4 v[128:131], v[132:133], off offset:528
	global_load_dwordx4 v[172:175], v[184:185], off offset:2048
	global_load_dwordx4 v[176:179], v[184:185], off offset:-2048
	global_load_dwordx4 v[140:143], v[132:133], off offset:16
	s_nop 0
	global_load_dwordx4 v[132:135], v[132:133], off offset:512
	s_nop 0
	global_load_dwordx4 v[180:183], v[184:185], off offset:2560
	s_nop 0
	global_load_dwordx4 v[184:187], v[184:185], off offset:-1536
	s_nop 0
	global_load_dwordx4 v[188:191], v[200:201], off offset:-2048
	global_load_dwordx4 v[192:195], v[200:201], off offset:2048
	global_load_dwordx4 v[196:199], v[200:201], off offset:-1536
	s_nop 0
	global_load_dwordx4 v[200:203], v[200:201], off offset:2560
	v_lshl_add_u64 v[216:217], v[162:163], 0, v[238:239]
	v_or_b32_e32 v220, 48, v220
	global_load_dwordx4 v[204:207], v[216:217], off offset:-2048
	global_load_dwordx4 v[208:211], v[216:217], off offset:2048
	global_load_dwordx4 v[212:215], v[216:217], off offset:-1536
	s_nop 0
	global_load_dwordx4 v[216:219], v[216:217], off offset:2560
	v_ashrrev_i32_e32 v221, 31, v220
	v_lshlrev_b64 v[240:241], 12, v[220:221]
	v_lshl_add_u64 v[232:233], v[162:163], 0, v[240:241]
	global_load_dwordx4 v[220:223], v[232:233], off offset:-2048
	global_load_dwordx4 v[224:227], v[232:233], off offset:2048
	global_load_dwordx4 v[228:231], v[232:233], off offset:-1536
	s_nop 0
	global_load_dwordx4 v[232:235], v[232:233], off offset:2560
	v_lshl_add_u64 v[242:243], s[66:67], 0, v[164:165]
	v_lshl_add_u64 v[242:243], v[242:243], 0, v[160:161]
	v_lshl_add_u64 v[236:237], s[66:67], 0, v[236:237]
	v_lshl_add_u64 v[244:245], v[164:165], 0, s[12:13]
	v_lshl_add_u64 v[236:237], v[236:237], 0, v[160:161]
	v_lshl_add_u64 v[246:247], v[162:163], 0, v[244:245]
	s_andn2_b64 s[74:75], exec, s[0:1]
	s_mov_b64 s[0:1], -1
	s_mov_b32 vcc_lo, 0x55555555
	s_mov_b32 vcc_hi, 0x55555555
	v_mov_b32_dpp v248, v124 quad_perm:[1,0,3,2] row_mask:0xf bank_mask:0xf
	v_cndmask_b32_dpp v124, v120, v124, vcc quad_perm:[1,0,3,2] row_mask:0xf bank_mask:0xf
	v_cndmask_b32_e32 v120, v120, v248, vcc
	v_mov_b32_dpp v249, v125 quad_perm:[1,0,3,2] row_mask:0xf bank_mask:0xf
	v_cndmask_b32_dpp v125, v121, v125, vcc quad_perm:[1,0,3,2] row_mask:0xf bank_mask:0xf
	v_cndmask_b32_e32 v121, v121, v249, vcc
	v_mov_b32_dpp v248, v126 quad_perm:[1,0,3,2] row_mask:0xf bank_mask:0xf
	v_cndmask_b32_dpp v126, v122, v126, vcc quad_perm:[1,0,3,2] row_mask:0xf bank_mask:0xf
	v_cndmask_b32_e32 v122, v122, v248, vcc
	v_mov_b32_dpp v249, v127 quad_perm:[1,0,3,2] row_mask:0xf bank_mask:0xf
	v_cndmask_b32_dpp v127, v123, v127, vcc quad_perm:[1,0,3,2] row_mask:0xf bank_mask:0xf
	v_cndmask_b32_e32 v123, v123, v249, vcc
	v_mov_b32_dpp v248, v108 quad_perm:[1,0,3,2] row_mask:0xf bank_mask:0xf
	v_cndmask_b32_dpp v108, v104, v108, vcc quad_perm:[1,0,3,2] row_mask:0xf bank_mask:0xf
	v_cndmask_b32_e32 v104, v104, v248, vcc
	v_mov_b32_dpp v249, v109 quad_perm:[1,0,3,2] row_mask:0xf bank_mask:0xf
	v_cndmask_b32_dpp v109, v105, v109, vcc quad_perm:[1,0,3,2] row_mask:0xf bank_mask:0xf
	v_cndmask_b32_e32 v105, v105, v249, vcc
	v_mov_b32_dpp v248, v110 quad_perm:[1,0,3,2] row_mask:0xf bank_mask:0xf
	v_cndmask_b32_dpp v110, v106, v110, vcc quad_perm:[1,0,3,2] row_mask:0xf bank_mask:0xf
	v_cndmask_b32_e32 v106, v106, v248, vcc
	v_mov_b32_dpp v249, v111 quad_perm:[1,0,3,2] row_mask:0xf bank_mask:0xf
	v_cndmask_b32_dpp v111, v107, v111, vcc quad_perm:[1,0,3,2] row_mask:0xf bank_mask:0xf
	v_cndmask_b32_e32 v107, v107, v249, vcc
	v_mov_b32_dpp v248, v116 quad_perm:[1,0,3,2] row_mask:0xf bank_mask:0xf
	v_cndmask_b32_dpp v116, v112, v116, vcc quad_perm:[1,0,3,2] row_mask:0xf bank_mask:0xf
	v_cndmask_b32_e32 v112, v112, v248, vcc
	v_mov_b32_dpp v249, v117 quad_perm:[1,0,3,2] row_mask:0xf bank_mask:0xf
	v_cndmask_b32_dpp v117, v113, v117, vcc quad_perm:[1,0,3,2] row_mask:0xf bank_mask:0xf
	v_cndmask_b32_e32 v113, v113, v249, vcc
	v_mov_b32_dpp v248, v118 quad_perm:[1,0,3,2] row_mask:0xf bank_mask:0xf
	v_cndmask_b32_dpp v118, v114, v118, vcc quad_perm:[1,0,3,2] row_mask:0xf bank_mask:0xf
; #define EO_LOAD(bt_) do { _Pragma("unroll") for (int mm = 0; mm < 2; ++mm) { const float* xr = xbase + (size_t)(row0 + ((bt_) >> 1) * 128 + (2 * ((bt_) & 1) + mm) * 16) * DM + col0; \
;             _Pragma("unroll") for (int bj = 0; bj < 2; ++bj) _Pragma("unroll") for (int n = 0; n < 2; ++n) xv[(bt_) & 1][mm][bj][n] = *(const f32x4*)(xr + 128 * bj + 4 * n); } } while (0)
; #define EO_FENCE() asm volatile("" ::: "memory")
;     __device__ __forceinline__ void operator()(const f32x4 (&acc)[2][2][4][2], const pg8::Unit& u, int wr, int wc, int fr, int fq) const {
;     ...
;         f32x4 xv[2][2][2][2];
;     ...
;         EO_LOAD(0); EO_FENCE(); EO_LOAD(1); EO_FENCE();
;         EO_STORE(0); EO_FENCE(); EO_LOAD(2); EO_FENCE();
;         EO_STORE(1); EO_FENCE(); EO_LOAD(3); EO_FENCE();
;         EO_STORE(2); EO_FENCE(); EO_STORE(3);
	v_cndmask_b32_e32 v114, v114, v248, vcc
	v_mov_b32_dpp v249, v119 quad_perm:[1,0,3,2] row_mask:0xf bank_mask:0xf
	v_cndmask_b32_dpp v119, v115, v119, vcc quad_perm:[1,0,3,2] row_mask:0xf bank_mask:0xf
	v_cndmask_b32_e32 v115, v115, v249, vcc
	v_mov_b32_dpp v248, v100 quad_perm:[1,0,3,2] row_mask:0xf bank_mask:0xf
	v_cndmask_b32_dpp v100, v92, v100, vcc quad_perm:[1,0,3,2] row_mask:0xf bank_mask:0xf
	v_cndmask_b32_e32 v92, v92, v248, vcc
	v_mov_b32_dpp v249, v101 quad_perm:[1,0,3,2] row_mask:0xf bank_mask:0xf
	v_cndmask_b32_dpp v101, v93, v101, vcc quad_perm:[1,0,3,2] row_mask:0xf bank_mask:0xf
	v_cndmask_b32_e32 v93, v93, v249, vcc
	v_mov_b32_dpp v248, v102 quad_perm:[1,0,3,2] row_mask:0xf bank_mask:0xf
	v_cndmask_b32_dpp v102, v94, v102, vcc quad_perm:[1,0,3,2] row_mask:0xf bank_mask:0xf
	v_cndmask_b32_e32 v94, v94, v248, vcc
	v_mov_b32_dpp v249, v103 quad_perm:[1,0,3,2] row_mask:0xf bank_mask:0xf
	v_cndmask_b32_dpp v103, v95, v103, vcc quad_perm:[1,0,3,2] row_mask:0xf bank_mask:0xf
	v_cndmask_b32_e32 v95, v95, v249, vcc
	v_mov_b32_dpp v248, v96 quad_perm:[1,0,3,2] row_mask:0xf bank_mask:0xf
	v_cndmask_b32_dpp v96, v88, v96, vcc quad_perm:[1,0,3,2] row_mask:0xf bank_mask:0xf
	v_cndmask_b32_e32 v88, v88, v248, vcc
	v_mov_b32_dpp v249, v97 quad_perm:[1,0,3,2] row_mask:0xf bank_mask:0xf
	v_cndmask_b32_dpp v97, v89, v97, vcc quad_perm:[1,0,3,2] row_mask:0xf bank_mask:0xf
	v_cndmask_b32_e32 v89, v89, v249, vcc
	v_mov_b32_dpp v248, v98 quad_perm:[1,0,3,2] row_mask:0xf bank_mask:0xf
	v_cndmask_b32_dpp v98, v90, v98, vcc quad_perm:[1,0,3,2] row_mask:0xf bank_mask:0xf
	v_cndmask_b32_e32 v90, v90, v248, vcc
	v_mov_b32_dpp v249, v99 quad_perm:[1,0,3,2] row_mask:0xf bank_mask:0xf
	v_cndmask_b32_dpp v99, v91, v99, vcc quad_perm:[1,0,3,2] row_mask:0xf bank_mask:0xf
	v_cndmask_b32_e32 v91, v91, v249, vcc
	v_mov_b32_dpp v248, v80 quad_perm:[1,0,3,2] row_mask:0xf bank_mask:0xf
	v_cndmask_b32_dpp v80, v72, v80, vcc quad_perm:[1,0,3,2] row_mask:0xf bank_mask:0xf
	v_cndmask_b32_e32 v72, v72, v248, vcc
	v_mov_b32_dpp v249, v81 quad_perm:[1,0,3,2] row_mask:0xf bank_mask:0xf
	v_cndmask_b32_dpp v81, v73, v81, vcc quad_perm:[1,0,3,2] row_mask:0xf bank_mask:0xf
	v_cndmask_b32_e32 v73, v73, v249, vcc
	v_mov_b32_dpp v248, v82 quad_perm:[1,0,3,2] row_mask:0xf bank_mask:0xf
	v_cndmask_b32_dpp v82, v74, v82, vcc quad_perm:[1,0,3,2] row_mask:0xf bank_mask:0xf
	v_cndmask_b32_e32 v74, v74, v248, vcc
	v_mov_b32_dpp v249, v83 quad_perm:[1,0,3,2] row_mask:0xf bank_mask:0xf
	v_cndmask_b32_dpp v83, v75, v83, vcc quad_perm:[1,0,3,2] row_mask:0xf bank_mask:0xf
	v_cndmask_b32_e32 v75, v75, v249, vcc
	v_mov_b32_dpp v248, v84 quad_perm:[1,0,3,2] row_mask:0xf bank_mask:0xf
	v_cndmask_b32_dpp v84, v76, v84, vcc quad_perm:[1,0,3,2] row_mask:0xf bank_mask:0xf
	v_cndmask_b32_e32 v76, v76, v248, vcc
	v_mov_b32_dpp v249, v85 quad_perm:[1,0,3,2] row_mask:0xf bank_mask:0xf
	v_cndmask_b32_dpp v85, v77, v85, vcc quad_perm:[1,0,3,2] row_mask:0xf bank_mask:0xf
	v_cndmask_b32_e32 v77, v77, v249, vcc
	v_mov_b32_dpp v248, v86 quad_perm:[1,0,3,2] row_mask:0xf bank_mask:0xf
	v_cndmask_b32_dpp v86, v78, v86, vcc quad_perm:[1,0,3,2] row_mask:0xf bank_mask:0xf
	v_cndmask_b32_e32 v78, v78, v248, vcc
	v_mov_b32_dpp v249, v87 quad_perm:[1,0,3,2] row_mask:0xf bank_mask:0xf
	v_cndmask_b32_dpp v87, v79, v87, vcc quad_perm:[1,0,3,2] row_mask:0xf bank_mask:0xf
	v_cndmask_b32_e32 v79, v79, v249, vcc
	v_mov_b32_dpp v248, v68 quad_perm:[1,0,3,2] row_mask:0xf bank_mask:0xf
	v_cndmask_b32_dpp v68, v64, v68, vcc quad_perm:[1,0,3,2] row_mask:0xf bank_mask:0xf
	v_cndmask_b32_e32 v64, v64, v248, vcc
	v_mov_b32_dpp v249, v69 quad_perm:[1,0,3,2] row_mask:0xf bank_mask:0xf
	v_cndmask_b32_dpp v69, v65, v69, vcc quad_perm:[1,0,3,2] row_mask:0xf bank_mask:0xf
	v_cndmask_b32_e32 v65, v65, v249, vcc
	v_mov_b32_dpp v248, v70 quad_perm:[1,0,3,2] row_mask:0xf bank_mask:0xf
	v_cndmask_b32_dpp v70, v66, v70, vcc quad_perm:[1,0,3,2] row_mask:0xf bank_mask:0xf
	v_cndmask_b32_e32 v66, v66, v248, vcc
	v_mov_b32_dpp v249, v71 quad_perm:[1,0,3,2] row_mask:0xf bank_mask:0xf
	v_cndmask_b32_dpp v71, v67, v71, vcc quad_perm:[1,0,3,2] row_mask:0xf bank_mask:0xf
	v_cndmask_b32_e32 v67, v67, v249, vcc
	v_mov_b32_dpp v248, v60 quad_perm:[1,0,3,2] row_mask:0xf bank_mask:0xf
	v_cndmask_b32_dpp v60, v56, v60, vcc quad_perm:[1,0,3,2] row_mask:0xf bank_mask:0xf
	v_cndmask_b32_e32 v56, v56, v248, vcc
	v_mov_b32_dpp v249, v61 quad_perm:[1,0,3,2] row_mask:0xf bank_mask:0xf
	v_cndmask_b32_dpp v61, v57, v61, vcc quad_perm:[1,0,3,2] row_mask:0xf bank_mask:0xf
	v_cndmask_b32_e32 v57, v57, v249, vcc
	v_mov_b32_dpp v248, v62 quad_perm:[1,0,3,2] row_mask:0xf bank_mask:0xf
	v_cndmask_b32_dpp v62, v58, v62, vcc quad_perm:[1,0,3,2] row_mask:0xf bank_mask:0xf
	v_cndmask_b32_e32 v58, v58, v248, vcc
	v_mov_b32_dpp v249, v63 quad_perm:[1,0,3,2] row_mask:0xf bank_mask:0xf
	v_cndmask_b32_dpp v63, v59, v63, vcc quad_perm:[1,0,3,2] row_mask:0xf bank_mask:0xf
	v_cndmask_b32_e32 v59, v59, v249, vcc
	v_mov_b32_dpp v248, v44 quad_perm:[1,0,3,2] row_mask:0xf bank_mask:0xf
	v_cndmask_b32_dpp v44, v40, v44, vcc quad_perm:[1,0,3,2] row_mask:0xf bank_mask:0xf
	v_cndmask_b32_e32 v40, v40, v248, vcc
	v_mov_b32_dpp v249, v45 quad_perm:[1,0,3,2] row_mask:0xf bank_mask:0xf
	v_cndmask_b32_dpp v45, v41, v45, vcc quad_perm:[1,0,3,2] row_mask:0xf bank_mask:0xf
	v_cndmask_b32_e32 v41, v41, v249, vcc
	v_mov_b32_dpp v248, v46 quad_perm:[1,0,3,2] row_mask:0xf bank_mask:0xf
	v_cndmask_b32_dpp v46, v42, v46, vcc quad_perm:[1,0,3,2] row_mask:0xf bank_mask:0xf
	v_cndmask_b32_e32 v42, v42, v248, vcc
	v_mov_b32_dpp v249, v47 quad_perm:[1,0,3,2] row_mask:0xf bank_mask:0xf
; #define EO_LOAD(bt_) do { _Pragma("unroll") for (int mm = 0; mm < 2; ++mm) { const float* xr = xbase + (size_t)(row0 + ((bt_) >> 1) * 128 + (2 * ((bt_) & 1) + mm) * 16) * DM + col0; \
;             _Pragma("unroll") for (int bj = 0; bj < 2; ++bj) _Pragma("unroll") for (int n = 0; n < 2; ++n) xv[(bt_) & 1][mm][bj][n] = *(const f32x4*)(xr + 128 * bj + 4 * n); } } while (0)
; #define EO_FENCE() asm volatile("" ::: "memory")
;     __device__ __forceinline__ void operator()(const f32x4 (&acc)[2][2][4][2], const pg8::Unit& u, int wr, int wc, int fr, int fq) const {
;     ...
;         f32x4 xv[2][2][2][2];
;     ...
;         EO_LOAD(0); EO_FENCE(); EO_LOAD(1); EO_FENCE();
;         EO_STORE(0); EO_FENCE(); EO_LOAD(2); EO_FENCE();
;         EO_STORE(1); EO_FENCE(); EO_LOAD(3); EO_FENCE();
;         EO_STORE(2); EO_FENCE(); EO_STORE(3);
	v_cndmask_b32_dpp v47, v43, v47, vcc quad_perm:[1,0,3,2] row_mask:0xf bank_mask:0xf
	v_cndmask_b32_e32 v43, v43, v249, vcc
	v_mov_b32_dpp v248, v52 quad_perm:[1,0,3,2] row_mask:0xf bank_mask:0xf
	v_cndmask_b32_dpp v52, v48, v52, vcc quad_perm:[1,0,3,2] row_mask:0xf bank_mask:0xf
	v_cndmask_b32_e32 v48, v48, v248, vcc
	v_mov_b32_dpp v249, v53 quad_perm:[1,0,3,2] row_mask:0xf bank_mask:0xf
	v_cndmask_b32_dpp v53, v49, v53, vcc quad_perm:[1,0,3,2] row_mask:0xf bank_mask:0xf
	v_cndmask_b32_e32 v49, v49, v249, vcc
	v_mov_b32_dpp v248, v54 quad_perm:[1,0,3,2] row_mask:0xf bank_mask:0xf
	v_cndmask_b32_dpp v54, v50, v54, vcc quad_perm:[1,0,3,2] row_mask:0xf bank_mask:0xf
	v_cndmask_b32_e32 v50, v50, v248, vcc
	v_mov_b32_dpp v249, v55 quad_perm:[1,0,3,2] row_mask:0xf bank_mask:0xf
	v_cndmask_b32_dpp v55, v51, v55, vcc quad_perm:[1,0,3,2] row_mask:0xf bank_mask:0xf
	v_cndmask_b32_e32 v51, v51, v249, vcc
	v_mov_b32_dpp v248, v32 quad_perm:[1,0,3,2] row_mask:0xf bank_mask:0xf
	v_cndmask_b32_dpp v32, v28, v32, vcc quad_perm:[1,0,3,2] row_mask:0xf bank_mask:0xf
	v_cndmask_b32_e32 v28, v28, v248, vcc
	v_mov_b32_dpp v249, v33 quad_perm:[1,0,3,2] row_mask:0xf bank_mask:0xf
	v_cndmask_b32_dpp v33, v29, v33, vcc quad_perm:[1,0,3,2] row_mask:0xf bank_mask:0xf
	v_cndmask_b32_e32 v29, v29, v249, vcc
	v_mov_b32_dpp v248, v34 quad_perm:[1,0,3,2] row_mask:0xf bank_mask:0xf
	v_cndmask_b32_dpp v34, v30, v34, vcc quad_perm:[1,0,3,2] row_mask:0xf bank_mask:0xf
	v_cndmask_b32_e32 v30, v30, v248, vcc
	v_mov_b32_dpp v249, v35 quad_perm:[1,0,3,2] row_mask:0xf bank_mask:0xf
	v_cndmask_b32_dpp v35, v31, v35, vcc quad_perm:[1,0,3,2] row_mask:0xf bank_mask:0xf
	v_cndmask_b32_e32 v31, v31, v249, vcc
	v_mov_b32_dpp v248, v36 quad_perm:[1,0,3,2] row_mask:0xf bank_mask:0xf
	v_cndmask_b32_dpp v36, v24, v36, vcc quad_perm:[1,0,3,2] row_mask:0xf bank_mask:0xf
	v_cndmask_b32_e32 v24, v24, v248, vcc
	v_mov_b32_dpp v249, v37 quad_perm:[1,0,3,2] row_mask:0xf bank_mask:0xf
	v_cndmask_b32_dpp v37, v25, v37, vcc quad_perm:[1,0,3,2] row_mask:0xf bank_mask:0xf
	v_cndmask_b32_e32 v25, v25, v249, vcc
	v_mov_b32_dpp v248, v38 quad_perm:[1,0,3,2] row_mask:0xf bank_mask:0xf
	v_cndmask_b32_dpp v38, v26, v38, vcc quad_perm:[1,0,3,2] row_mask:0xf bank_mask:0xf
	v_cndmask_b32_e32 v26, v26, v248, vcc
	v_mov_b32_dpp v249, v39 quad_perm:[1,0,3,2] row_mask:0xf bank_mask:0xf
	v_cndmask_b32_dpp v39, v27, v39, vcc quad_perm:[1,0,3,2] row_mask:0xf bank_mask:0xf
	v_cndmask_b32_e32 v27, v27, v249, vcc
	v_mov_b32_dpp v248, v16 quad_perm:[1,0,3,2] row_mask:0xf bank_mask:0xf
	v_cndmask_b32_dpp v16, v8, v16, vcc quad_perm:[1,0,3,2] row_mask:0xf bank_mask:0xf
	v_cndmask_b32_e32 v8, v8, v248, vcc
	v_mov_b32_dpp v249, v17 quad_perm:[1,0,3,2] row_mask:0xf bank_mask:0xf
	v_cndmask_b32_dpp v17, v9, v17, vcc quad_perm:[1,0,3,2] row_mask:0xf bank_mask:0xf
	v_cndmask_b32_e32 v9, v9, v249, vcc
	v_mov_b32_dpp v248, v18 quad_perm:[1,0,3,2] row_mask:0xf bank_mask:0xf
	v_cndmask_b32_dpp v18, v10, v18, vcc quad_perm:[1,0,3,2] row_mask:0xf bank_mask:0xf
	v_cndmask_b32_e32 v10, v10, v248, vcc
	v_mov_b32_dpp v249, v19 quad_perm:[1,0,3,2] row_mask:0xf bank_mask:0xf
	v_cndmask_b32_dpp v19, v11, v19, vcc quad_perm:[1,0,3,2] row_mask:0xf bank_mask:0xf
	v_cndmask_b32_e32 v11, v11, v249, vcc
	v_mov_b32_dpp v248, v20 quad_perm:[1,0,3,2] row_mask:0xf bank_mask:0xf
	v_cndmask_b32_dpp v20, v12, v20, vcc quad_perm:[1,0,3,2] row_mask:0xf bank_mask:0xf
	v_cndmask_b32_e32 v12, v12, v248, vcc
	v_mov_b32_dpp v249, v21 quad_perm:[1,0,3,2] row_mask:0xf bank_mask:0xf
	v_cndmask_b32_dpp v21, v13, v21, vcc quad_perm:[1,0,3,2] row_mask:0xf bank_mask:0xf
	v_cndmask_b32_e32 v13, v13, v249, vcc
	v_mov_b32_dpp v248, v22 quad_perm:[1,0,3,2] row_mask:0xf bank_mask:0xf
	v_cndmask_b32_dpp v22, v14, v22, vcc quad_perm:[1,0,3,2] row_mask:0xf bank_mask:0xf
	v_cndmask_b32_e32 v14, v14, v248, vcc
	v_mov_b32_dpp v249, v23 quad_perm:[1,0,3,2] row_mask:0xf bank_mask:0xf
	v_cndmask_b32_dpp v23, v15, v23, vcc quad_perm:[1,0,3,2] row_mask:0xf bank_mask:0xf
	v_cndmask_b32_e32 v15, v15, v249, vcc
	v_mov_b32_dpp v248, v4 quad_perm:[1,0,3,2] row_mask:0xf bank_mask:0xf
	v_cndmask_b32_dpp v4, v0, v4, vcc quad_perm:[1,0,3,2] row_mask:0xf bank_mask:0xf
	v_cndmask_b32_e32 v0, v0, v248, vcc
	v_mov_b32_dpp v249, v5 quad_perm:[1,0,3,2] row_mask:0xf bank_mask:0xf
	v_cndmask_b32_dpp v5, v1, v5, vcc quad_perm:[1,0,3,2] row_mask:0xf bank_mask:0xf
	v_cndmask_b32_e32 v1, v1, v249, vcc
	v_mov_b32_dpp v248, v6 quad_perm:[1,0,3,2] row_mask:0xf bank_mask:0xf
	v_cndmask_b32_dpp v6, v2, v6, vcc quad_perm:[1,0,3,2] row_mask:0xf bank_mask:0xf
	v_cndmask_b32_e32 v2, v2, v248, vcc
	v_mov_b32_dpp v249, v7 quad_perm:[1,0,3,2] row_mask:0xf bank_mask:0xf
	v_cndmask_b32_dpp v7, v3, v7, vcc quad_perm:[1,0,3,2] row_mask:0xf bank_mask:0xf
	v_cndmask_b32_e32 v3, v3, v249, vcc
	s_waitcnt vmcnt(8)
; #define EO_LOAD(bt_) do { _Pragma("unroll") for (int mm = 0; mm < 2; ++mm) { const float* xr = xbase + (size_t)(row0 + ((bt_) >> 1) * 128 + (2 * ((bt_) & 1) + mm) * 16) * DM + col0; \
;             _Pragma("unroll") for (int bj = 0; bj < 2; ++bj) _Pragma("unroll") for (int n = 0; n < 2; ++n) xv[(bt_) & 1][mm][bj][n] = *(const f32x4*)(xr + 128 * bj + 4 * n); } } while (0)
; #define EO_FENCE() asm volatile("" ::: "memory")
;     __device__ __forceinline__ void operator()(const f32x4 (&acc)[2][2][4][2], const pg8::Unit& u, int wr, int wc, int fr, int fq) const {
;     ...
;         EO_LOAD(0); EO_FENCE(); EO_LOAD(1); EO_FENCE();
;         EO_STORE(0); EO_FENCE(); EO_LOAD(2); EO_FENCE();
;         EO_STORE(1); EO_FENCE(); EO_LOAD(3); EO_FENCE();
;         EO_STORE(2); EO_FENCE(); EO_STORE(3);
	v_cndmask_b32_e32 v136, v140, v136, vcc
	v_cndmask_b32_e32 v132, v128, v132, vcc
	v_cndmask_b32_e32 v137, v141, v137, vcc
	v_cndmask_b32_e32 v133, v129, v133, vcc
	v_cndmask_b32_e32 v138, v142, v138, vcc
	v_cndmask_b32_e32 v134, v130, v134, vcc
	v_cndmask_b32_e32 v139, v143, v139, vcc
	v_cndmask_b32_e32 v135, v131, v135, vcc
	v_mov_b32_e32 v140, v136
	v_mov_b32_e32 v128, v132
	v_mov_b32_e32 v141, v137
	v_mov_b32_e32 v129, v133
	v_mov_b32_e32 v142, v138
	v_mov_b32_e32 v130, v134
	v_mov_b32_e32 v143, v139
	v_mov_b32_e32 v131, v135
	v_pk_fma_f32 v[122:123], v[122:123], v[142:143], v[174:175]
	v_pk_fma_f32 v[126:127], v[126:127], v[138:139], v[178:179]
	v_pk_fma_f32 v[124:125], v[124:125], v[136:137], v[176:177]
	v_pk_fma_f32 v[120:121], v[120:121], v[140:141], v[172:173]
	v_pk_fma_f32 v[110:111], v[110:111], v[134:135], v[186:187]
	v_pk_fma_f32 v[108:109], v[108:109], v[132:133], v[184:185]
	v_pk_fma_f32 v[106:107], v[106:107], v[130:131], v[182:183]
	v_pk_fma_f32 v[104:105], v[104:105], v[128:129], v[180:181]
	v_pk_fma_f32 v[118:119], v[118:119], v[138:139], v[190:191]
	v_pk_fma_f32 v[116:117], v[116:117], v[136:137], v[188:189]
	v_pk_fma_f32 v[114:115], v[114:115], v[142:143], v[194:195]
	v_pk_fma_f32 v[112:113], v[112:113], v[140:141], v[192:193]
	v_pk_fma_f32 v[102:103], v[102:103], v[134:135], v[198:199]
	v_pk_fma_f32 v[100:101], v[100:101], v[132:133], v[196:197]
	v_pk_fma_f32 v[94:95], v[94:95], v[130:131], v[202:203]
	v_pk_fma_f32 v[92:93], v[92:93], v[128:129], v[200:201]
	global_store_dwordx4 v[242:243], v[124:127], off offset:-2048
	global_store_dwordx4 v[242:243], v[120:123], off offset:2048
	global_store_dwordx4 v[242:243], v[108:111], off offset:-1536
	global_store_dwordx4 v[242:243], v[104:107], off offset:2560
	global_store_dwordx4 v[236:237], v[116:119], off offset:-2048
	global_store_dwordx4 v[236:237], v[112:115], off offset:2048
	global_store_dwordx4 v[236:237], v[100:103], off offset:-1536
	global_store_dwordx4 v[236:237], v[92:95], off offset:2560
	v_lshl_add_u64 v[172:173], v[164:165], 0, s[14:15]
	v_lshl_add_u64 v[174:175], s[66:67], 0, v[238:239]
	v_lshl_add_u64 v[124:125], v[162:163], 0, v[172:173]
	v_lshl_add_u64 v[174:175], v[174:175], 0, v[160:161]
	s_waitcnt vmcnt(8)
	v_pk_fma_f32 v[74:75], v[74:75], v[130:131], v[218:219]
	v_pk_fma_f32 v[72:73], v[72:73], v[128:129], v[216:217]
	global_load_dwordx4 v[92:95], v[246:247], off offset:2048
	global_load_dwordx4 v[100:103], v[246:247], off offset:-2048
	global_load_dwordx4 v[104:107], v[246:247], off offset:2560
	global_load_dwordx4 v[108:111], v[246:247], off offset:-1536
	global_load_dwordx4 v[112:115], v[124:125], off offset:2048
	global_load_dwordx4 v[116:119], v[124:125], off offset:-2048
	global_load_dwordx4 v[120:123], v[124:125], off offset:2560
	s_nop 0
	global_load_dwordx4 v[124:127], v[124:125], off offset:-1536
	v_pk_fma_f32 v[82:83], v[82:83], v[134:135], v[214:215]
	v_pk_fma_f32 v[80:81], v[80:81], v[132:133], v[212:213]
	global_store_dwordx4 v[174:175], v[72:75], off offset:2560
	global_store_dwordx4 v[174:175], v[80:83], off offset:-1536
	v_pk_fma_f32 v[98:99], v[98:99], v[138:139], v[206:207]
	v_lshl_add_u64 v[72:73], s[66:67], 0, v[240:241]
	v_lshl_add_u64 v[80:81], v[72:73], 0, v[160:161]
	v_pk_fma_f32 v[74:75], v[86:87], v[138:139], v[222:223]
	v_pk_fma_f32 v[72:73], v[84:85], v[136:137], v[220:221]
	v_pk_fma_f32 v[96:97], v[96:97], v[136:137], v[204:205]
	v_pk_fma_f32 v[90:91], v[90:91], v[142:143], v[210:211]
	v_pk_fma_f32 v[88:89], v[88:89], v[140:141], v[208:209]
	global_store_dwordx4 v[80:81], v[72:75], off offset:-2048
	v_pk_fma_f32 v[70:71], v[70:71], v[134:135], v[230:231]
	v_pk_fma_f32 v[68:69], v[68:69], v[132:133], v[228:229]
	v_pk_fma_f32 v[74:75], v[78:79], v[142:143], v[226:227]
	v_pk_fma_f32 v[72:73], v[76:77], v[140:141], v[224:225]
	v_pk_fma_f32 v[66:67], v[66:67], v[130:131], v[234:235]
	v_pk_fma_f32 v[64:65], v[64:65], v[128:129], v[232:233]
	global_store_dwordx4 v[174:175], v[96:99], off offset:-2048
	global_store_dwordx4 v[174:175], v[88:91], off offset:2048
	global_store_dwordx4 v[80:81], v[72:75], off offset:2048
	global_store_dwordx4 v[80:81], v[68:71], off offset:-1536
	global_store_dwordx4 v[80:81], v[64:67], off offset:2560
	v_lshl_add_u64 v[174:175], v[164:165], 0, s[16:17]
	v_lshl_add_u64 v[76:77], v[162:163], 0, v[174:175]
	global_load_dwordx4 v[64:67], v[76:77], off offset:-2048
	global_load_dwordx4 v[68:71], v[76:77], off offset:2048
	global_load_dwordx4 v[72:75], v[76:77], off offset:-1536
	s_nop 0
	global_load_dwordx4 v[76:79], v[76:77], off offset:2560
	v_lshl_add_u64 v[164:165], v[164:165], 0, s[18:19]
	v_lshl_add_u64 v[96:97], v[162:163], 0, v[164:165]
	global_load_dwordx4 v[80:83], v[96:97], off offset:-2048
	global_load_dwordx4 v[84:87], v[96:97], off offset:2048
	global_load_dwordx4 v[88:91], v[96:97], off offset:-1536
	s_nop 0
	global_load_dwordx4 v[96:99], v[96:97], off offset:2560
	v_lshl_add_u64 v[162:163], s[66:67], 0, v[244:245]
	v_lshl_add_u64 v[172:173], s[66:67], 0, v[172:173]
	v_lshl_add_u64 v[174:175], s[66:67], 0, v[174:175]
	v_lshl_add_u64 v[162:163], v[162:163], 0, v[160:161]
	v_lshl_add_u64 v[172:173], v[172:173], 0, v[160:161]
	v_lshl_add_u64 v[174:175], v[174:175], 0, v[160:161]
	s_waitcnt vmcnt(23)
; #define PG8_BAR __builtin_amdgcn_s_barrier()
; #define EO_LOAD(bt_) do { _Pragma("unroll") for (int mm = 0; mm < 2; ++mm) { const float* xr = xbase + (size_t)(row0 + ((bt_) >> 1) * 128 + (2 * ((bt_) & 1) + mm) * 16) * DM + col0; \
;             _Pragma("unroll") for (int bj = 0; bj < 2; ++bj) _Pragma("unroll") for (int n = 0; n < 2; ++n) xv[(bt_) & 1][mm][bj][n] = *(const f32x4*)(xr + 128 * bj + 4 * n); } } while (0)
; #define EO_FENCE() asm volatile("" ::: "memory")
; template <class Epi, class Sched, bool ALIGN_EPI = false, bool SP2 = false>
; __device__ __forceinline__ void gemm_phase(PG8_LAS unsigned char* lds, const Gemm g, const Sched& S, const Epi& E) {
;     ...
;         if constexpr (ALIGN_EPI) { if (wr == 0) PG8_BAR; }
;         if constexpr (!Epi::AFTER_DRAIN) { E(acc, cur, wr, wc, fr, fq); S.done(cur); }
;         if (!has_next) break;
; #pragma unroll
;         for (int a = 0; a < 2; ++a)
; #pragma unroll
;             for (int b = 0; b < 2; ++b)
; #pragma unroll
;                 for (int m = 0; m < 4; ++m)
; #pragma unroll
;                     for (int n = 0; n < 2; ++n) acc[a][b][m][n] = (f32x4){0.f, 0.f, 0.f, 0.f};
;         cur = nxt; cA = nA; cB = nB; ++ui;
;         if constexpr (ALIGN_EPI) { if (wr == 1) PG8_BAR; }
;     __device__ __forceinline__ void operator()(const f32x4 (&acc)[2][2][4][2], const pg8::Unit& u, int wr, int wc, int fr, int fq) const {
;     ...
;         EO_LOAD(0); EO_FENCE(); EO_LOAD(1); EO_FENCE();
;         EO_STORE(0); EO_FENCE(); EO_LOAD(2); EO_FENCE();
;         EO_STORE(1); EO_FENCE(); EO_LOAD(3); EO_FENCE();
;         EO_STORE(2); EO_FENCE(); EO_STORE(3);
	v_pk_fma_f32 v[58:59], v[58:59], v[142:143], v[94:95]
	s_waitcnt vmcnt(22)
	v_pk_fma_f32 v[62:63], v[62:63], v[138:139], v[102:103]
	v_pk_fma_f32 v[60:61], v[60:61], v[136:137], v[100:101]
	v_pk_fma_f32 v[56:57], v[56:57], v[140:141], v[92:93]
	s_waitcnt vmcnt(20)
	v_pk_fma_f32 v[46:47], v[46:47], v[134:135], v[110:111]
	v_pk_fma_f32 v[44:45], v[44:45], v[132:133], v[108:109]
	v_pk_fma_f32 v[42:43], v[42:43], v[130:131], v[106:107]
	v_pk_fma_f32 v[40:41], v[40:41], v[128:129], v[104:105]
	s_waitcnt vmcnt(18)
	v_pk_fma_f32 v[54:55], v[54:55], v[138:139], v[118:119]
	v_pk_fma_f32 v[52:53], v[52:53], v[136:137], v[116:117]
	v_pk_fma_f32 v[50:51], v[50:51], v[142:143], v[114:115]
	v_pk_fma_f32 v[48:49], v[48:49], v[140:141], v[112:113]
	s_waitcnt vmcnt(16)
	v_pk_fma_f32 v[34:35], v[34:35], v[134:135], v[126:127]
	v_pk_fma_f32 v[32:33], v[32:33], v[132:133], v[124:125]
	v_pk_fma_f32 v[30:31], v[30:31], v[130:131], v[122:123]
	v_pk_fma_f32 v[28:29], v[28:29], v[128:129], v[120:121]
	global_store_dwordx4 v[162:163], v[60:63], off offset:-2048
	global_store_dwordx4 v[162:163], v[56:59], off offset:2048
	global_store_dwordx4 v[162:163], v[44:47], off offset:-1536
	global_store_dwordx4 v[162:163], v[40:43], off offset:2560
	global_store_dwordx4 v[172:173], v[52:55], off offset:-2048
	global_store_dwordx4 v[172:173], v[48:51], off offset:2048
	global_store_dwordx4 v[172:173], v[32:35], off offset:-1536
	global_store_dwordx4 v[172:173], v[28:31], off offset:2560
	s_waitcnt vmcnt(14)
	v_pk_fma_f32 v[26:27], v[26:27], v[142:143], v[70:71]
	s_waitcnt vmcnt(13)
	v_pk_fma_f32 v[18:19], v[18:19], v[134:135], v[74:75]
	s_waitcnt vmcnt(12)
	v_pk_fma_f32 v[10:11], v[10:11], v[130:131], v[78:79]
	v_pk_fma_f32 v[8:9], v[8:9], v[128:129], v[76:77]
	v_pk_fma_f32 v[16:17], v[16:17], v[132:133], v[72:73]
	global_store_dwordx4 v[174:175], v[8:11], off offset:2560
	global_store_dwordx4 v[174:175], v[16:19], off offset:-1536
	v_pk_fma_f32 v[30:31], v[38:39], v[138:139], v[66:67]
	v_lshl_add_u64 v[8:9], s[66:67], 0, v[164:165]
	v_lshl_add_u64 v[16:17], v[8:9], 0, v[160:161]
	s_waitcnt vmcnt(13)
	v_pk_fma_f32 v[10:11], v[22:23], v[138:139], v[82:83]
	v_pk_fma_f32 v[8:9], v[20:21], v[136:137], v[80:81]
	v_pk_fma_f32 v[28:29], v[36:37], v[136:137], v[64:65]
	v_pk_fma_f32 v[24:25], v[24:25], v[140:141], v[68:69]
	global_store_dwordx4 v[16:17], v[8:11], off offset:-2048
	s_waitcnt vmcnt(12)
	v_pk_fma_f32 v[6:7], v[6:7], v[134:135], v[90:91]
	v_pk_fma_f32 v[4:5], v[4:5], v[132:133], v[88:89]
	v_pk_fma_f32 v[10:11], v[14:15], v[142:143], v[86:87]
	v_pk_fma_f32 v[8:9], v[12:13], v[140:141], v[84:85]
	s_waitcnt vmcnt(11)
	v_pk_fma_f32 v[2:3], v[2:3], v[130:131], v[98:99]
	v_pk_fma_f32 v[0:1], v[0:1], v[128:129], v[96:97]
	global_store_dwordx4 v[174:175], v[28:31], off offset:-2048
	global_store_dwordx4 v[174:175], v[24:27], off offset:2048
	global_store_dwordx4 v[16:17], v[8:11], off offset:2048
	global_store_dwordx4 v[16:17], v[4:7], off offset:-1536
	global_store_dwordx4 v[16:17], v[0:3], off offset:2560
	s_mov_b64 vcc, s[74:75]
	s_cbranch_vccnz .LBB0_453
	s_andn2_b64 vcc, exec, s[4:5]
	s_cbranch_vccnz .LBB0_452
	s_barrier
	s_branch .LBB0_452
